# attention phase: four-group workgroup stagger (0/3.5/7/10.5 us) keyed on block-index bits 3 and 4
# baseline (speedup 1.0000x reference)
; DI void phase_attn1(const Params& p, char* smem) {
;   const int G = gridDim.x;
;   for (int round = 0; round * G < 512; ++round) {
;     const int j = (round & 1) ? (G - 1 - (int)blockIdx.x) : (int)blockIdx.x;
;     const int t = round * G + j;
;     if (t >= 512) continue;
;     const int qt = 15 - (t >> 5), bh = t & 31;
;     mla_item(p, bh >> 3, bh & 7, qt, smem);
;   }
.LBB0_1361:
	s_or_b64 exec, exec, s[0:1]
	s_not_b32 s0, s84
	s_add_i32 s27, s96, s0
	s_add_u32 s24, s22, 0x154c0000
	s_addc_u32 s25, s23, 0
	s_add_u32 s33, s22, 0x184c0000
	s_addc_u32 s40, s23, 0
	s_add_u32 s41, s22, 0x1a4c0000
	s_addc_u32 s44, s23, 0
	s_add_u32 s45, s22, 0x1a6c0000
	s_addc_u32 s46, s23, 0
	s_add_u32 s28, s22, 0x40c0000
	s_movk_i32 s34, 0xff00
	s_addc_u32 s29, s23, 0
	s_mov_b32 s31, 0
	s_movk_i32 s47, 0xc00
	v_mov_b32_e32 v0, 0
	s_mov_b32 s48, 0x2aaaaaab
	s_mov_b32 s35, -1
	s_movk_i32 s49, 0x190
	s_movk_i32 s50, 0x88
	s_movk_i32 s51, 0x6400
	s_mov_b32 s52, 0xf149f2ca
	s_mov_b32 s53, 0x3dd53b94
	s_mov_b32 s54, 0x41000000
	s_mov_b64 s[36:37], 0x20000
	s_mov_b64 s[38:39], 0x2000
	s_movk_i32 s55, 0x3300
	s_mov_b64 s[42:43], 0x80c0a00
	s_mov_b32 s56, 0x80c0000
	v_mov_b32_e32 v199, 0xf149f2ca
	v_mbcnt_hi_u32_b32 v198, -1, v207
	s_mov_b32 s0, 0
	s_mov_b32 s57, 0
	v_readlane_b32 s98, v252, 38
	s_bitcmp1_b32 s98, 6
	s_cbranch_scc0 .Lstag_10
	s_sleep 127
.Lstag_10:
	s_bitcmp1_b32 s98, 7
	s_cbranch_scc0 .Lstag_10b
	s_sleep 127
	s_sleep 127
.Lstag_10b:
	s_waitcnt lgkmcnt(0)
	s_barrier
	s_branch .LBB0_1365
